# plus: attention K/V LDS-DMA destinations formed on the scalar unit (M0 from one per-phase base) instead of 9 VALU per tile
# baseline (speedup 1.0000x reference)
; DI float shx(float v, int o, int lane) { return __int_as_float(__builtin_amdgcn_ds_bpermute((lane ^ o) << 2, __float_as_int(v))); }
; DI int ltid(int wv) { int l; asm volatile("v_mbcnt_lo_u32_b32 %0, -1, 0\n\tv_mbcnt_hi_u32_b32 %0, -1, %0" : "=v"(l)); return wv * 64 + l; }
; DI void phase_attn(const Params& p, int j, float lam_init, bool last, unsigned char* shm, int wv, int slot) {
;   const u16* QKB = (const u16*)(p.ws + R_QKB);
;   const u16* VT = (const u16*)(p.ws + R_VT);
;   u16* OB = (u16*)(p.ws + R_MIX);
;   const int tid = ltid(wv), lane = tid & 63, w = tid >> 6;
;   const int r = lane & 31, hh = lane >> 5, qsub = w >> 1, map = w & 1;
;   float lam;
;   {
;     const float* lp = p.in[26] + j * 256;
;     float a = lp[lane] * lp[64 + lane], b = lp[128 + lane] * lp[192 + lane];
;     a = wave_sum(a, lane); b = wave_sum(b, lane);
;     lam = __expf(a) - __expf(b) + lam_init;
;   }
;   bool fastsm;
;   {
;     float gq = fabsf(p.in[24][j * 64 + lane]), gk = fabsf(p.in[25][j * 64 + lane]);
; #pragma unroll
;     for (int o = 32; o >= 1; o >>= 1) { gq = fmaxf(gq, shx(gq, o, lane)); gk = fmaxf(gk, shx(gk, o, lane)); }
;     const float bound = 11.6f * gq * gk;
;     fastsm = __builtin_amdgcn_readfirstlane((int)(bound <= 100.f)) != 0;
;   }
;   const float* ghead = p.in[27] + j * 128;
;   const int ntask = 4096 + (last ? 0 : 512);
;   const int nb = gridDim.x;
;   const int krow = tid >> 3, kch = tid & 7;
;   if (wv >= 4) __builtin_amdgcn_s_setprio(1);
;   for (int task = slot; task < ntask; task += nb) {
;     int b, head, qrow0, kt0, nkt;
;     if (task < 4096) { b = task >> 7; head = (task >> 4) & 7; qrow0 = b * 2048 + (task & 15) * 128; kt0 = 0; nkt = 36; }
;     else { int t2 = task - 4096; b = t2 >> 4; head = (t2 >> 1) & 7; qrow0 = NX + b * 256 + (t2 & 1) * 128; kt0 = 32; nkt = 4; }
.LBB0_521:
	v_readlane_b32 s0, v255, 31
	v_readlane_b32 s1, v255, 32
	s_and_b64 s[6:7], s[0:1], exec
	s_movk_i32 s1, 0x1000
	s_cselect_b32 s43, s1, 0x1200
	v_readlane_b32 s0, v252, 2
	s_cmp_ge_i32 s0, s43
	v_readlane_b32 s16, v255, 22
	s_mov_b32 s35, s53
	s_cbranch_scc1 .LBB0_586
	v_readlane_b32 s0, v255, 39
	v_add_f32_e32 v4, v4, v5
	v_add_f32_e32 v5, v6, v7
	v_cvt_f32_u32_e32 v0, s0
	s_mov_b32 s0, 0x3fb8aa3b
	v_mul_f32_e32 v4, 0x3fb8aa3b, v4
	v_mul_f32_e32 v5, 0x3fb8aa3b, v5
	v_mul_f32_e32 v0, 0xbe99999a, v0
	v_mul_f32_e32 v8, 0x3fb8aa3b, v0
	v_fma_f32 v9, v0, s0, -v8
	v_rndne_f32_e32 v10, v8
	v_fmac_f32_e32 v9, 0x32a5705f, v0
	v_sub_f32_e32 v8, v8, v10
	v_add_f32_e32 v8, v8, v9
	v_exp_f32_e32 v8, v8
	v_cvt_i32_f32_e32 v9, v10
	s_mov_b32 s0, 0xc2ce8ed0
	v_exp_f32_e32 v4, v4
	v_exp_f32_e32 v5, v5
	v_ldexp_f32 v8, v8, v9
	v_cmp_ngt_f32_e32 vcc, s0, v0
	s_mov_b32 s0, 0x42b17218
	v_add_u32_e32 v10, s53, v3
	v_cndmask_b32_e32 v8, 0, v8, vcc
	v_cmp_nlt_f32_e32 vcc, s0, v0
	v_mov_b32_e32 v0, 0x7f800000
	v_sub_f32_e32 v4, v4, v5
	v_cndmask_b32_e32 v0, v0, v8, vcc
	v_mov_b32_e32 v8, 0x3f4ccccd
	v_fmamk_f32 v8, v0, 0xbf19999a, v8
	v_ashrrev_i32_e32 v0, 6, v10
	v_add_f32_e32 v114, v8, v4
	v_lshrrev_b32_e32 v4, 3, v2
	v_readlane_b32 s1, v255, 40
	v_lshl_or_b32 v121, v0, 3, v4
	v_readlane_b32 s10, v255, 0
	v_readlane_b32 s0, v255, 41
	v_lshrrev_b32_e32 v4, 1, v121
	v_readlane_b32 s11, v255, 1
	s_lshl_b32 s10, s0, 7
	v_readlane_b32 s16, v251, 0
	v_xor_b32_e32 v4, v4, v3
	s_xor_b64 s[8:9], s[4:5], -1
	s_lshl_b64 s[4:5], s[10:11], 2
	v_readlane_b32 s18, v251, 2
	v_readlane_b32 s22, v251, 6
	v_lshlrev_b32_e32 v4, 3, v4
	v_readlane_b32 s19, v251, 3
	v_readlane_b32 s23, v251, 7
	s_add_u32 s18, s22, s4
	v_and_b32_e32 v116, 56, v4
	v_mov_b64_e32 v[4:5], s[94:95]
	s_movk_i32 s0, 0x1200
	v_readlane_b32 s1, v255, 42
	s_addc_u32 s19, s23, s5
	v_mad_i64_i32 v[118:119], s[4:5], v121, s0, v[4:5]
	v_lshlrev_b32_e32 v4, 4, v2
	v_and_b32_e32 v7, 1, v0
	v_lshl_or_b32 v152, v0, 10, v4
	v_ashrrev_i32_e32 v0, 2, v10
	s_movk_i32 s1, 0xffe0
	v_lshrrev_b32_e32 v9, 5, v2
	v_and_b32_e32 v6, 31, v3
	v_bfi_b32 v155, s1, v0, v3
	s_movk_i32 s1, 0x210
	s_movk_i32 s0, 0x110
	v_lshrrev_b32_e32 v5, 1, v3
	v_bfe_u32 v11, v3, 1, 3
	v_lshlrev_b32_e32 v120, 3, v9
	v_lshl_add_u32 v157, v6, 7, 16
	v_mul_lo_u32 v0, v155, s1
	v_mul_lo_u32 v6, v155, s0
	v_readlane_b32 s1, v254, 63
	v_and_b32_e32 v3, 15, v3
	v_mov_b32_e32 v15, 0x42800000
	v_add_u32_e32 v159, s1, v6
	v_lshl_add_u32 v12, v3, 4, s1
	v_lshlrev_b32_e32 v6, 3, v3
	v_cvt_f32_ubyte0_e32 v3, v120
	v_mul_f32_e32 v14, 0xbf549a78, v3
	s_mov_b32 s1, 0xc2fc0000
	v_cmp_gt_f32_e32 vcc, s1, v14
	v_not_b32_e32 v16, 63
	v_sub_f32_e32 v158, 1.0, v8
	v_cndmask_b32_e32 v14, 0, v15, vcc
	v_fmac_f32_e32 v14, 0xbf549a78, v3
	v_exp_f32_e32 v3, v14
	v_cndmask_b32_e32 v14, 0, v16, vcc
	v_ashrrev_i32_e32 v8, 4, v10
	v_lshlrev_b32_e32 v4, 6, v7
	v_ldexp_f32 v160, v3, v14
	v_or_b32_e32 v3, 1, v120
	v_cvt_f32_ubyte0_e32 v3, v3
	v_mul_f32_e32 v14, 0xbf549a78, v3
	v_cmp_gt_f32_e32 vcc, s1, v14
	v_cmp_eq_u32_e64 s[4:5], 0, v7
	v_cmp_eq_u32_e64 s[6:7], 1, v7
	v_cndmask_b32_e32 v14, 0, v15, vcc
	v_fmac_f32_e32 v14, 0xbf549a78, v3
	v_exp_f32_e32 v3, v14
	v_cndmask_b32_e32 v14, 0, v16, vcc
	v_add_u32_e32 v7, 16, v0
	v_lshlrev_b32_e32 v0, 4, v9
	v_ldexp_f32 v161, v3, v14
	v_or_b32_e32 v3, 2, v120
	v_cvt_f32_ubyte0_e32 v3, v3
	v_mul_f32_e32 v14, 0xbf549a78, v3
	v_cmp_gt_f32_e32 vcc, s1, v14
	v_mul_lo_u32 v13, v8, s0
	s_mov_b32 s13, s11
	v_cndmask_b32_e32 v14, 0, v15, vcc
	v_fmac_f32_e32 v14, 0xbf549a78, v3
	v_exp_f32_e32 v3, v14
	v_cndmask_b32_e32 v14, 0, v16, vcc
	s_lshl_b64 s[12:13], s[12:13], 2
	v_readlane_b32 s17, v251, 1
	v_ldexp_f32 v162, v3, v14
	v_or_b32_e32 v3, 3, v120
	v_cvt_f32_ubyte0_e32 v3, v3
	v_mul_f32_e32 v14, 0xbf549a78, v3
	v_cmp_gt_f32_e32 vcc, s1, v14
; DI void phase_attn(const Params& p, int j, float lam_init, bool last, unsigned char* shm, int wv, int slot) {
;     ...
;     const int drow = w * 8 + (lane >> 3); const int dcg = (lane & 7) ^ ((drow >> 1) & 7);
;     const u16* kptr = QKB + (size_t)((kt0 < 32) ? (b * 2048 + kt0 * 64 + drow) : (NX + b * 256 + (kt0 - 32) * 64 + drow)) * 2048 + 1024 + head * 128 + dcg * 8;
;     const u16* vptr = vbase + (size_t)drow * 2304 + kt0 * 64 + dcg * 8;
;     const u16* vptr2 = vptr + (size_t)64 * 2304;
;     const unsigned ldsoff = w * 1024 + lane * 16;
;     int dma_kt = kt0;
;     ...
;     const int swz = ((r >> 1) & 7);
;     ...
;         for (int jq = 0; jq < 8; ++jq) {
;           const float invf = exp2f(-(float)(hh * 8 + jq) * 0.8304820237218406f);
;           float sn, cs;
	s_add_u32 s12, s16, s12
	v_add_u32_e32 v153, 16, v152
	v_cndmask_b32_e32 v14, 0, v15, vcc
	v_readfirstlane_b32 s100, v153
	v_fmac_f32_e32 v14, 0xbf549a78, v3
	v_exp_f32_e32 v3, v14
	v_cndmask_b32_e32 v14, 0, v16, vcc
	v_or_b32_e32 v17, 0x60, v120
	v_or_b32_e32 v18, 0x70, v120
	v_ldexp_f32 v163, v3, v14
	v_or_b32_e32 v3, 4, v120
	v_cvt_f32_ubyte0_e32 v3, v3
	v_mul_f32_e32 v14, 0xbf549a78, v3
	v_cmp_gt_f32_e32 vcc, s1, v14
	v_or_b32_e32 v19, 0x80, v120
	v_or_b32_e32 v20, 0x90, v120
	v_cndmask_b32_e32 v14, 0, v15, vcc
	v_fmac_f32_e32 v14, 0xbf549a78, v3
	v_exp_f32_e32 v3, v14
	v_cndmask_b32_e32 v14, 0, v16, vcc
	v_or_b32_e32 v21, 0xa0, v120
	v_or_b32_e32 v22, 0xb0, v120
	v_ldexp_f32 v164, v3, v14
	v_or_b32_e32 v3, 5, v120
	v_cvt_f32_ubyte0_e32 v3, v3
	v_mul_f32_e32 v14, 0xbf549a78, v3
	v_cmp_gt_f32_e32 vcc, s1, v14
	v_or_b32_e32 v23, 0xc0, v120
	v_or_b32_e32 v24, 0xd0, v120
	v_cndmask_b32_e32 v14, 0, v15, vcc
	v_fmac_f32_e32 v14, 0xbf549a78, v3
	v_exp_f32_e32 v3, v14
	v_cndmask_b32_e32 v14, 0, v16, vcc
	v_or_b32_e32 v25, 0xe0, v120
	v_or_b32_e32 v26, 0xf0, v120
	v_ldexp_f32 v165, v3, v14
	v_or_b32_e32 v3, 6, v120
	v_cvt_f32_ubyte0_e32 v3, v3
	v_mul_f32_e32 v14, 0xbf549a78, v3
	v_cmp_gt_f32_e32 vcc, s1, v14
	s_addc_u32 s13, s17, s13
	v_and_b32_e32 v2, 32, v2
	v_cndmask_b32_e32 v14, 0, v15, vcc
	v_fmac_f32_e32 v14, 0xbf549a78, v3
	v_exp_f32_e32 v3, v14
	v_cndmask_b32_e32 v14, 0, v16, vcc
	v_add_u32_e32 v154, 0xc000, v153
	v_add_u32_e32 v156, 0x10000, v121
	v_ldexp_f32 v166, v3, v14
	v_or_b32_e32 v3, 7, v120
	v_cvt_f32_ubyte0_e32 v3, v3
	v_mul_f32_e32 v14, 0xbf549a78, v3
	v_cmp_gt_f32_e32 vcc, s1, v14
	v_lshl_add_u64 v[122:123], s[18:19], 0, v[0:1]
	v_mov_b32_e32 v115, v114
	v_cndmask_b32_e32 v14, 0, v15, vcc
	v_fmac_f32_e32 v14, 0xbf549a78, v3
	v_exp_f32_e32 v3, v14
	v_cndmask_b32_e32 v14, 0, v16, vcc
	v_or_b32_e32 v15, 64, v120
	v_or_b32_e32 v16, 0x50, v120
	v_ldexp_f32 v167, v3, v14
	v_bitop3_b32 v3, v9, v11, 6 bitop3:0x36
	v_lshlrev_b32_e32 v168, 4, v3
	v_bitop3_b32 v3, v9, v11, 4 bitop3:0x36
	v_lshlrev_b32_e32 v169, 4, v3
	v_bitop3_b32 v3, v9, v11, 2 bitop3:0x36
	v_lshlrev_b32_e32 v170, 4, v3
	v_bitop3_b32 v3, v9, v5, 7 bitop3:0x78
	v_lshlrev_b32_e32 v171, 4, v3
	v_ashrrev_i32_e32 v9, 31, v8
	v_add_u32_e32 v3, 0x200, v10
	v_lshlrev_b64 v[124:125], 11, v[8:9]
	v_ashrrev_i32_e32 v8, 4, v3
	v_ashrrev_i32_e32 v9, 31, v8
	v_add_u32_e32 v3, 0x400, v10
	v_mul_lo_u32 v27, v8, s0
	v_lshlrev_b64 v[126:127], 11, v[8:9]
	v_ashrrev_i32_e32 v8, 4, v3
	v_ashrrev_i32_e32 v9, 31, v8
	v_add_u32_e32 v3, 0x600, v10
	v_mul_lo_u32 v28, v8, s0
	v_lshlrev_b64 v[128:129], 11, v[8:9]
	v_ashrrev_i32_e32 v8, 4, v3
	v_or_b32_e32 v5, 16, v120
	v_or_b32_e32 v11, 32, v120
	v_or_b32_e32 v14, 48, v120
	v_mul_lo_u32 v10, v8, s0
	v_ashrrev_i32_e32 v9, 31, v8
	v_mov_b32_e32 v3, v1
	v_lshlrev_b64 v[130:131], 11, v[8:9]
	v_lshl_add_u64 v[132:133], s[12:13], 0, v[2:3]
	v_lshlrev_b32_e32 v134, 1, v4
	v_add_u32_e32 v172, v159, v5
	v_add_u32_e32 v173, v159, v11
	v_add_u32_e32 v174, v159, v14
	v_add_u32_e32 v175, v159, v15
	v_add_u32_e32 v176, v159, v16
	v_add_u32_e32 v177, v159, v17
	v_add_u32_e32 v178, v159, v18
	v_add_u32_e32 v179, v159, v19
	v_add_u32_e32 v193, v159, v20
	v_add_u32_e32 v194, v159, v21
	v_add_u32_e32 v195, v159, v22
	v_add_u32_e32 v196, v159, v23
	v_add_u32_e32 v197, v159, v24
	v_add_u32_e32 v198, v159, v25
	v_add_u32_e32 v199, v159, v26
	v_lshlrev_b32_e32 v136, 1, v6
	v_add_u32_e32 v200, v12, v13
	v_add_u32_e32 v201, v12, v27
	v_add_u32_e32 v202, v12, v28
	v_add_u32_e32 v203, v12, v10
	v_add_u32_e32 v204, v7, v0
	v_readlane_b32 s96, v252, 2
	s_mov_b32 s0, 0x41000000
	s_mov_b64 s[28:29], 0x800
	s_mov_b32 s16, 0x3e38aa3b
	s_mov_b64 s[30:31], 0x40000
	s_mov_b64 s[38:39], 0x80
	v_readlane_b32 s20, v251, 4
	v_readlane_b32 s21, v251, 5
	s_branch .LBB0_524

.LBB0_569:
	s_cmp_ge_u32 s22, s13
	s_cselect_b64 s[18:19], -1, 0
	s_and_b64 vcc, exec, s[18:19]
	s_cbranch_vccnz .LBB0_571
	s_lshl_b32 s20, s1, 14
	s_addk_i32 s20, 0xc000
	s_cmp_lg_u32 s1, 0
	s_cselect_b32 s20, s20, 0x8000
	s_add_i32 s20, s20, s100
	s_lshl_b32 s101, s17, 14
	s_mov_b32 m0, s20
	s_xor_b32 s101, s101, 0x8000
	s_add_i32 s101, s101, s100
	global_load_lds_dwordx4 v[144:145], off
	v_lshl_add_u64 v[82:83], v[144:145], 0, s[38:39]
	s_add_i32 m0, s20, 0x2000
	s_add_i32 s20, s101, 0xc000
	global_load_lds_dwordx4 v[82:83], off
	s_mov_b32 m0, s20
	s_add_i32 s20, s101, 0xe000
	global_load_lds_dwordx4 v[140:141], off
	s_mov_b32 m0, s20
	s_add_i32 s69, s69, 1
	global_load_lds_dwordx4 v[142:143], off
	s_cmp_eq_u32 s69, 32
	v_lshl_add_u64 v[82:83], v[144:145], 0, s[30:31]
	s_cselect_b64 vcc, -1, 0
	v_lshl_add_u64 v[140:141], v[140:141], 0, s[38:39]
	v_lshl_add_u64 v[142:143], v[142:143], 0, s[38:39]
	v_cndmask_b32_e32 v145, v83, v139, vcc
	v_cndmask_b32_e32 v144, v82, v138, vcc

; __global__ void __launch_bounds__(512) mega(Params p) {
;   extern __shared__ __attribute__((aligned(16))) unsigned char shm[];
	.amdhsa_kernel _Z4mega6Params
		.amdhsa_group_segment_fixed_size 16
		.amdhsa_private_segment_fixed_size 0
		.amdhsa_kernarg_size 496
		.amdhsa_user_sgpr_count 2
		.amdhsa_user_sgpr_dispatch_ptr 0
		.amdhsa_user_sgpr_queue_ptr 0
		.amdhsa_user_sgpr_kernarg_segment_ptr 1
		.amdhsa_user_sgpr_dispatch_id 0
		.amdhsa_user_sgpr_kernarg_preload_length 0
		.amdhsa_user_sgpr_kernarg_preload_offset 0
		.amdhsa_user_sgpr_private_segment_size 0
		.amdhsa_uses_dynamic_stack 0
		.amdhsa_enable_private_segment 0
		.amdhsa_system_sgpr_workgroup_id_x 1
		.amdhsa_system_sgpr_workgroup_id_y 0
		.amdhsa_system_sgpr_workgroup_id_z 0
		.amdhsa_system_sgpr_workgroup_info 0
		.amdhsa_system_vgpr_workitem_id 2
		.amdhsa_next_free_vgpr 256
		.amdhsa_next_free_sgpr 102
		.amdhsa_accum_offset 256
		.amdhsa_reserve_vcc 1
		.amdhsa_float_round_mode_32 0
		.amdhsa_float_round_mode_16_64 0
		.amdhsa_float_denorm_mode_32 3
		.amdhsa_float_denorm_mode_16_64 3
		.amdhsa_dx10_clamp 1
		.amdhsa_ieee_mode 1
		.amdhsa_fp16_overflow 0
		.amdhsa_tg_split 0
		.amdhsa_exception_fp_ieee_invalid_op 0
		.amdhsa_exception_fp_denorm_src 0
		.amdhsa_exception_fp_ieee_div_zero 0
		.amdhsa_exception_fp_ieee_overflow 0
		.amdhsa_exception_fp_ieee_underflow 0
		.amdhsa_exception_fp_ieee_inexact 0
		.amdhsa_exception_int_div_zero 0
	.end_amdhsa_kernel

; __global__ void __launch_bounds__(512) mega(Params p) {
;   extern __shared__ __attribute__((aligned(16))) unsigned char shm[];
amdhsa.kernels:
  - .agpr_count:     0
    .args:
      - .offset:         0
        .size:           240
        .value_kind:     by_value
      - .offset:         240
        .size:           4
        .value_kind:     hidden_block_count_x
      - .offset:         244
        .size:           4
        .value_kind:     hidden_block_count_y
      - .offset:         248
        .size:           4
        .value_kind:     hidden_block_count_z
      - .offset:         252
        .size:           2
        .value_kind:     hidden_group_size_x
      - .offset:         254
        .size:           2
        .value_kind:     hidden_group_size_y
      - .offset:         256
        .size:           2
        .value_kind:     hidden_group_size_z
      - .offset:         258
        .size:           2
        .value_kind:     hidden_remainder_x
      - .offset:         260
        .size:           2
        .value_kind:     hidden_remainder_y
      - .offset:         262
        .size:           2
        .value_kind:     hidden_remainder_z
      - .offset:         280
        .size:           8
        .value_kind:     hidden_global_offset_x
      - .offset:         288
        .size:           8
        .value_kind:     hidden_global_offset_y
      - .offset:         296
        .size:           8
        .value_kind:     hidden_global_offset_z
      - .offset:         304
        .size:           2
        .value_kind:     hidden_grid_dims
      - .offset:         328
        .size:           8
        .value_kind:     hidden_multigrid_sync_arg
      - .offset:         360
        .size:           4
        .value_kind:     hidden_dynamic_lds_size
    .group_segment_fixed_size: 16
    .kernarg_segment_align: 8
    .kernarg_segment_size: 496
    .language:       OpenCL C
    .language_version:
      - 2
      - 0
    .max_flat_workgroup_size: 512
    .name:           _Z4mega6Params
    .private_segment_fixed_size: 0
    .sgpr_count:     108
    .sgpr_spill_count: 403
    .symbol:         _Z4mega6Params.kd
    .uniform_work_group_size: 1
    .uses_dynamic_stack: false
    .vgpr_count:     256
    .vgpr_spill_count: 0
    .wavefront_size: 64
